# stack12: stack11 + P4 cmp pass-B K-fragment ds_reads batched with counted lgkmcnt waits
# speedup vs baseline: 1.0159x; 1.0094x over previous
.LBB0_1325:
	s_and_b32 s7, s6, 1
	s_mul_i32 s2, s7, 0x2400
	v_add_u32_e32 v236, s2, v200
	ds_read_b128 v[106:109], v236
	ds_read_b128 v[110:113], v236 offset:4608
	ds_read_b128 v[114:117], v236 offset:32
	ds_read_b128 v[118:121], v236 offset:4640
	ds_read_b128 v[122:125], v236 offset:64
	ds_read_b128 v[126:129], v236 offset:4672
	ds_read_b128 v[130:133], v236 offset:96
	ds_read_b128 v[134:137], v236 offset:4704
	s_add_i32 s3, s5, 63
	s_cmp_le_i32 s3, s9
	s_waitcnt lgkmcnt(7)
	v_mfma_f32_32x32x16_bf16 v[66:81], v[106:109], v[94:97], v[2:17]
	s_waitcnt lgkmcnt(6)
	v_mfma_f32_32x32x16_bf16 v[50:65], v[110:113], v[94:97], v[2:17]
	s_waitcnt lgkmcnt(5)
	v_mfma_f32_32x32x16_bf16 v[66:81], v[114:117], v[86:89], v[66:81]
	s_waitcnt lgkmcnt(4)
	v_mfma_f32_32x32x16_bf16 v[50:65], v[118:121], v[86:89], v[50:65]
	s_waitcnt lgkmcnt(3)
	v_mfma_f32_32x32x16_bf16 v[66:81], v[122:125], v[90:93], v[66:81]
	s_waitcnt lgkmcnt(2)
	v_mfma_f32_32x32x16_bf16 v[50:65], v[126:129], v[90:93], v[50:65]
	s_waitcnt lgkmcnt(1)
	v_mfma_f32_32x32x16_bf16 v[66:81], v[130:133], v[98:101], v[66:81]
	s_waitcnt lgkmcnt(0)
	v_mfma_f32_32x32x16_bf16 v[50:65], v[134:137], v[98:101], v[50:65]
	s_cbranch_scc1 .LBB0_1327
	v_add_u32_e32 v106, s5, v142
	v_cmp_lt_i32_e32 vcc, v106, v233
	v_add_u32_e32 v107, 2, v106
	s_nop 4
	v_cndmask_b32_e32 v67, v207, v67, vcc
	v_cmp_le_i32_e32 vcc, v106, v233
	s_nop 1
	v_cndmask_b32_e32 v66, v207, v66, vcc
	v_cmp_lt_i32_e32 vcc, v106, v234
	s_nop 1
	v_cndmask_b32_e32 v51, v207, v51, vcc
	v_cmp_le_i32_e32 vcc, v106, v234
	s_nop 1
	v_cndmask_b32_e32 v50, v207, v50, vcc
	v_cmp_le_i32_e32 vcc, v107, v233
	s_nop 1
	v_cndmask_b32_e32 v68, v207, v68, vcc
	v_cmp_le_i32_e32 vcc, v107, v234
	v_add_u32_e32 v107, 3, v106
	s_nop 0
	v_cndmask_b32_e32 v52, v207, v52, vcc
	v_cmp_le_i32_e32 vcc, v107, v233
	s_nop 1
	v_cndmask_b32_e32 v69, v207, v69, vcc
	v_cmp_le_i32_e32 vcc, v107, v234
	v_add_u32_e32 v107, 8, v106
	s_nop 0
	v_cndmask_b32_e32 v53, v207, v53, vcc
	v_cmp_le_i32_e32 vcc, v107, v233
	s_nop 1
	v_cndmask_b32_e32 v70, v207, v70, vcc
	v_cmp_le_i32_e32 vcc, v107, v234
	v_add_u32_e32 v107, 9, v106
	s_nop 0
	v_cndmask_b32_e32 v54, v207, v54, vcc
	v_cmp_le_i32_e32 vcc, v107, v233
	s_nop 1
	v_cndmask_b32_e32 v71, v207, v71, vcc
	v_cmp_le_i32_e32 vcc, v107, v234
	v_add_u32_e32 v107, 10, v106
	s_nop 0
	v_cndmask_b32_e32 v55, v207, v55, vcc
	v_cmp_le_i32_e32 vcc, v107, v233
	s_nop 1
	v_cndmask_b32_e32 v72, v207, v72, vcc
	v_cmp_le_i32_e32 vcc, v107, v234
	v_add_u32_e32 v107, 11, v106
	s_nop 0
	v_cndmask_b32_e32 v56, v207, v56, vcc
	v_cmp_le_i32_e32 vcc, v107, v233
	s_nop 1
	v_cndmask_b32_e32 v73, v207, v73, vcc
	v_cmp_le_i32_e32 vcc, v107, v234
	v_add_u32_e32 v107, 16, v106
	s_nop 0
	v_cndmask_b32_e32 v57, v207, v57, vcc
	v_cmp_le_i32_e32 vcc, v107, v233
	s_nop 1
	v_cndmask_b32_e32 v74, v207, v74, vcc
	v_cmp_le_i32_e32 vcc, v107, v234
	v_add_u32_e32 v107, 17, v106
	s_nop 0
	v_cndmask_b32_e32 v58, v207, v58, vcc
	v_cmp_le_i32_e32 vcc, v107, v233
	s_nop 1
	v_cndmask_b32_e32 v75, v207, v75, vcc
	v_cmp_le_i32_e32 vcc, v107, v234
	v_add_u32_e32 v107, 18, v106
	s_nop 0
	v_cndmask_b32_e32 v59, v207, v59, vcc
	v_cmp_le_i32_e32 vcc, v107, v233
	s_nop 1
	v_cndmask_b32_e32 v76, v207, v76, vcc
	v_cmp_le_i32_e32 vcc, v107, v234
	v_add_u32_e32 v107, 19, v106
	s_nop 0
	v_cndmask_b32_e32 v60, v207, v60, vcc
	v_cmp_le_i32_e32 vcc, v107, v233
	s_nop 1
	v_cndmask_b32_e32 v77, v207, v77, vcc
	v_cmp_le_i32_e32 vcc, v107, v234
	v_add_u32_e32 v107, 24, v106
	s_nop 0
	v_cndmask_b32_e32 v61, v207, v61, vcc
	v_cmp_le_i32_e32 vcc, v107, v233
	s_nop 1
	v_cndmask_b32_e32 v78, v207, v78, vcc
	v_cmp_le_i32_e32 vcc, v107, v234
	v_add_u32_e32 v107, 25, v106
	s_nop 0
	v_cndmask_b32_e32 v62, v207, v62, vcc
	v_cmp_le_i32_e32 vcc, v107, v233
	s_nop 1
	v_cndmask_b32_e32 v79, v207, v79, vcc
	v_cmp_le_i32_e32 vcc, v107, v234
	v_add_u32_e32 v107, 26, v106
	v_add_u32_e32 v106, 27, v106
	v_cndmask_b32_e32 v63, v207, v63, vcc
	v_cmp_le_i32_e32 vcc, v107, v233
	s_nop 1
	v_cndmask_b32_e32 v80, v207, v80, vcc
	v_cmp_le_i32_e32 vcc, v107, v234
	s_nop 1
	v_cndmask_b32_e32 v64, v207, v64, vcc
	v_cmp_le_i32_e32 vcc, v106, v233
	s_nop 1
	v_cndmask_b32_e32 v81, v207, v81, vcc
	v_cmp_le_i32_e32 vcc, v106, v234
	s_nop 1
	v_cndmask_b32_e32 v65, v207, v65, vcc
